# v17: v16 plus log-sigmoid result consumed directly by the subtract (8 copies removed per item)
# speedup vs baseline: 1.0086x; 1.0001x over previous
; #define LAS __attribute__((address_space(3)))
; __device__ __forceinline__ void phase_gla_pre(const Params& P, LAS unsigned char* lds, bool dry) {
;     ...
;         for (int tt = 0; tt < 4; ++tt) {
;             bf16x8 ahi = (bf16x8){0, 0, 0, 0, 0, 0, 0, 0}, alo = ahi;
;             if (g < 2) { const f32x4 l0 = *(const LAS f32x4*)(Llr + (16 * tt + fr) * 16 + 8 * g), l1 = *(const LAS f32x4*)(Llr + (16 * tt + fr) * 16 + 8 * g + 4); split8(l0, l1, ahi, alo); }
;             f32x4 acc = (f32x4){bg, bg, bg, bg};
;             acc = __builtin_amdgcn_mfma_f32_16x16x32_bf16(alo, bhi, acc, 0, 0, 0); acc = __builtin_amdgcn_mfma_f32_16x16x32_bf16(ahi, blo, acc, 0, 0, 0); acc = __builtin_amdgcn_mfma_f32_16x16x32_bf16(ahi, bhi, acc, 0, 0, 0);
;             float pr[4];
; #pragma unroll
;             for (int r = 0; r < 4; ++r) { const float lg = acc[r]; const float ls = fminf(lg, 0.f) - __logf(1.0f + __expf(-fabsf(lg))); pr[r] = ls * (1.0f / 16.0f) + (r ? pr[r - 1] : 0.f); }
;             const float T = pr[3];
;             const float u1 = __shfl_up(T, 16), s1 = T + (g >= 1 ? u1 : 0.f);
;             const float u2 = __shfl_up(s1, 32), s2 = s1 + (g >= 2 ? u2 : 0.f);
;             const float base = run + (s2 - T); run += __shfl(s2, 48 + fr);
; #pragma unroll
;             for (int r = 0; r < 4; ++r) *(LAS float*)(Lb + (16 * tt + 4 * g + r) * BP + (16 * w + fr) * 4) = base + pr[r];
;         }
.Lp2_nowait1:
	v_mov_b32_e32 v140, v20
	v_mov_b32_e32 v141, v21
	v_mov_b32_e32 v142, v22
	v_mov_b32_e32 v143, v23
	v_mov_b32_e32 v144, v24
	v_mov_b32_e32 v145, v25
	v_mov_b32_e32 v146, v26
	v_mov_b32_e32 v147, v27
	v_mov_b32_e32 v148, v28
	s_and_b32 s98, s38, 0xff
	s_cselect_b32 s98, 0, 1
	v_mov_b32_e32 v29, v28
	v_mov_b32_e32 v30, v28
	v_mov_b32_e32 v31, v28
	s_nop 1
	v_mfma_f32_16x16x32_bf16 v[32:35], v[100:103], v[20:23], v[28:31]
	v_mfma_f32_16x16x32_bf16 v[32:35], v[104:107], v[24:27], v[32:35]
	v_mfma_f32_16x16x32_bf16 v[32:35], v[104:107], v[20:23], v[32:35]
	s_nop 7
	v_min_f32_e32 v36, 0, v32
	v_mul_f32_e64 v32, |v32|, s89
	v_exp_f32_e32 v32, v32
	v_mul_f32_e64 v37, |v33|, s89
	v_exp_f32_e32 v37, v37
	v_add_f32_e32 v32, 1.0, v32
	v_add_f32_e32 v37, 1.0, v37
	v_log_f32_e32 v32, v32
	v_log_f32_e32 v37, v37
	v_mul_f32_e32 v39, 0x3f317217, v32
	v_fma_f32 v39, v32, s91, -v39
	v_fmac_f32_e32 v39, 0x3377d1cf, v32
	v_fmac_f32_e32 v39, 0x3f317217, v32
	v_min_f32_e32 v33, 0, v33
	v_sub_f32_e32 v32, v36, v39
	v_mul_f32_e32 v36, 0x3f317217, v37
	v_fma_f32 v36, v37, s91, -v36
	v_fmac_f32_e32 v36, 0x3377d1cf, v37
	v_fmac_f32_e32 v36, 0x3f317217, v37
	v_fma_f32 v32, v32, s93, 0
	v_mul_f32_e64 v37, |v34|, s89
	v_exp_f32_e32 v37, v37
	v_sub_f32_e32 v33, v33, v36
	v_add_f32_e32 v36, 1.0, v37
	s_nop 1
	v_log_f32_e32 v36, v36
	v_fmamk_f32 v37, v33, 0x3d800000, v32
	v_min_f32_e32 v33, 0, v34
	v_mul_f32_e32 v34, 0x3f317217, v36
	v_fma_f32 v34, v36, s91, -v34
	v_fmac_f32_e32 v34, 0x3377d1cf, v36
	v_fmac_f32_e32 v34, 0x3f317217, v36
	s_nop 0
	v_mul_f32_e64 v36, |v35|, s89
	v_exp_f32_e32 v36, v36
	v_sub_f32_e32 v33, v33, v34
	v_add_u32_e32 v38, 0x8800, v98
	v_add_f32_e32 v34, 1.0, v36
	s_nop 1
	v_log_f32_e32 v34, v34
	v_fmamk_f32 v36, v33, 0x3d800000, v37
	v_min_f32_e32 v33, 0, v35
	v_mul_f32_e32 v35, 0x3f317217, v34
	v_fma_f32 v35, v34, s91, -v35
	v_fmac_f32_e32 v35, 0x3377d1cf, v34
	v_fmac_f32_e32 v35, 0x3f317217, v34
	s_nop 1
	v_sub_f32_e32 v33, v33, v35
	v_fmamk_f32 v34, v33, 0x3d800000, v36
	ds_bpermute_b32 v33, v83, v34
	s_waitcnt lgkmcnt(0)
	v_cndmask_b32_e64 v33, v33, 0, s[8:9]
	v_add_f32_e32 v33, v33, v34
	ds_bpermute_b32 v35, v84, v33
	s_waitcnt lgkmcnt(0)
	v_cndmask_b32_e64 v35, 0, v35, s[10:11]
	v_add_f32_e32 v33, v35, v33
	v_sub_f32_e32 v35, v33, v34
	ds_bpermute_b32 v33, v85, v33
	v_add_f32_e32 v35, 0, v35
	v_add_f32_e32 v32, v32, v35
	v_add_f32_e32 v37, v37, v35
	ds_write2_b32 v38, v32, v37 offset1:132
	v_add_f32_e32 v32, v36, v35
	v_add_f32_e32 v34, v34, v35
	v_add_u32_e32 v35, 0x8c00, v98
	ds_write2_b32 v35, v32, v34 offset0:8 offset1:140
	v_mov_b32_e32 v108, 0
	v_mov_b32_e32 v109, 0
	v_mov_b32_e32 v110, 0
	v_mov_b32_e32 v111, 0
	v_mov_b32_e32 v112, 0
	v_mov_b32_e32 v113, 0
	v_mov_b32_e32 v114, 0
	v_mov_b32_e32 v115, 0
	s_and_saveexec_b64 s[36:37], s[6:7]
	s_cbranch_execz .LBB0_488
	ds_read_b128 v[34:37], v96 offset:1024
	ds_read_b128 v[38:41], v96 offset:1040
	s_waitcnt lgkmcnt(1)
	v_cvt_pk_bf16_f32 v112, v34, v35
	v_lshlrev_b32_e32 v132, 16, v112
	v_and_b32_e32 v133, 0xffff0000, v112
	v_pk_add_f32 v[34:35], v[34:35], v[132:133] neg_lo:[0,1] neg_hi:[0,1]
	v_cvt_pk_bf16_f32 v113, v36, v37
	v_lshlrev_b32_e32 v134, 16, v113
	v_and_b32_e32 v135, 0xffff0000, v113
	v_pk_add_f32 v[36:37], v[36:37], v[134:135] neg_lo:[0,1] neg_hi:[0,1]
	s_waitcnt lgkmcnt(0)
	v_cvt_pk_bf16_f32 v114, v38, v39
	v_lshlrev_b32_e32 v136, 16, v114
	v_and_b32_e32 v137, 0xffff0000, v114
	v_pk_add_f32 v[38:39], v[38:39], v[136:137] neg_lo:[0,1] neg_hi:[0,1]
	v_cvt_pk_bf16_f32 v115, v40, v41
	v_lshlrev_b32_e32 v138, 16, v115
	v_and_b32_e32 v139, 0xffff0000, v115
	v_pk_add_f32 v[40:41], v[40:41], v[138:139] neg_lo:[0,1] neg_hi:[0,1]
	s_nop 0
	v_cvt_pk_bf16_f32 v111, v40, v41
	v_cvt_pk_bf16_f32 v110, v38, v39
	v_cvt_pk_bf16_f32 v109, v36, v37
	v_cvt_pk_bf16_f32 v108, v34, v35
.LBB0_488:
	s_or_b64 exec, exec, s[36:37]
	s_nop 0
	v_mfma_f32_16x16x32_bf16 v[34:37], v[108:111], v[20:23], v[28:31]
	v_mfma_f32_16x16x32_bf16 v[34:37], v[112:115], v[24:27], v[34:37]
	v_mfma_f32_16x16x32_bf16 v[34:37], v[112:115], v[20:23], v[34:37]
	s_nop 7
	v_min_f32_e32 v38, 0, v34
	v_mul_f32_e64 v34, |v34|, s89
	v_exp_f32_e32 v34, v34
	v_mul_f32_e64 v39, |v35|, s89
	v_exp_f32_e32 v39, v39
	v_add_f32_e32 v34, 1.0, v34
	v_add_f32_e32 v39, 1.0, v39
	v_log_f32_e32 v34, v34
	v_log_f32_e32 v39, v39
	v_mul_f32_e32 v41, 0x3f317217, v34
	v_fma_f32 v41, v34, s91, -v41
	v_fmac_f32_e32 v41, 0x3377d1cf, v34
	v_fmac_f32_e32 v41, 0x3f317217, v34
	v_mul_f32_e32 v42, 0x3f317217, v39
	v_sub_f32_e32 v34, v38, v41
	v_fma_f32 v38, v39, s91, -v42
	v_fmac_f32_e32 v38, 0x3377d1cf, v39
	v_fmac_f32_e32 v38, 0x3f317217, v39
	v_min_f32_e32 v35, 0, v35
	v_mul_f32_e64 v39, |v36|, s89
	v_exp_f32_e32 v39, v39
	v_sub_f32_e32 v35, v35, v38
	v_add_f32_e32 v38, 1.0, v39
	v_min_f32_e32 v36, 0, v36
	v_fma_f32 v34, v34, s93, 0
	v_log_f32_e32 v38, v38
	v_fmamk_f32 v35, v35, 0x3d800000, v34
	v_mul_f32_e32 v39, 0x3f317217, v38
	v_fma_f32 v39, v38, s91, -v39
	v_fmac_f32_e32 v39, 0x3377d1cf, v38
	v_fmac_f32_e32 v39, 0x3f317217, v38
	s_nop 1
	v_mov_b32_e32 v38, v39
	v_mul_f32_e64 v39, |v37|, s89
	v_exp_f32_e32 v39, v39
	v_sub_f32_e32 v36, v36, v38
	v_add_f32_e32 v38, 1.0, v39
	v_min_f32_e32 v37, 0, v37
	v_fmamk_f32 v36, v36, 0x3d800000, v35
	v_log_f32_e32 v38, v38
	s_waitcnt lgkmcnt(2)
	v_add_f32_e32 v40, 0, v33
	v_mul_f32_e32 v39, 0x3f317217, v38
	v_fma_f32 v39, v38, s91, -v39
	v_fmac_f32_e32 v39, 0x3377d1cf, v38
	v_fmac_f32_e32 v39, 0x3f317217, v38
	s_nop 1
	v_sub_f32_e32 v37, v37, v39
	v_fmamk_f32 v37, v37, 0x3d800000, v36
	ds_bpermute_b32 v38, v83, v37
	s_waitcnt lgkmcnt(0)
	v_cndmask_b32_e64 v38, v38, 0, s[8:9]
	v_add_f32_e32 v38, v38, v37
	ds_bpermute_b32 v39, v84, v38
	s_waitcnt lgkmcnt(0)
	v_cndmask_b32_e64 v33, 0, v39, s[10:11]
	v_add_f32_e32 v33, v33, v38
	v_sub_f32_e32 v38, v33, v37
	ds_bpermute_b32 v41, v85, v33
	v_add_f32_e32 v38, v40, v38
	v_add_f32_e32 v33, v34, v38
	v_add_f32_e32 v34, v35, v38
	v_add_u32_e32 v35, 0xa800, v98
	ds_write2_b32 v35, v33, v34 offset0:64 offset1:196
	v_add_f32_e32 v33, v36, v38
	v_add_f32_e32 v34, v37, v38
	v_add_u32_e32 v35, 0xac00, v98
	ds_write2_b32 v35, v33, v34 offset0:72 offset1:204
	v_mov_b32_e32 v116, 0
	v_mov_b32_e32 v117, 0
	v_mov_b32_e32 v118, 0
	v_mov_b32_e32 v119, 0
	v_mov_b32_e32 v120, 0
	v_mov_b32_e32 v121, 0
	v_mov_b32_e32 v122, 0
	v_mov_b32_e32 v123, 0
	s_and_saveexec_b64 s[36:37], s[6:7]
	s_cbranch_execz .LBB0_490
; #define LAS __attribute__((address_space(3)))
; __device__ __forceinline__ void phase_gla_pre(const Params& P, LAS unsigned char* lds, bool dry) {
;     ...
;         for (int tt = 0; tt < 4; ++tt) {
;             bf16x8 ahi = (bf16x8){0, 0, 0, 0, 0, 0, 0, 0}, alo = ahi;
;             if (g < 2) { const f32x4 l0 = *(const LAS f32x4*)(Llr + (16 * tt + fr) * 16 + 8 * g), l1 = *(const LAS f32x4*)(Llr + (16 * tt + fr) * 16 + 8 * g + 4); split8(l0, l1, ahi, alo); }
;             f32x4 acc = (f32x4){bg, bg, bg, bg};
;             acc = __builtin_amdgcn_mfma_f32_16x16x32_bf16(alo, bhi, acc, 0, 0, 0); acc = __builtin_amdgcn_mfma_f32_16x16x32_bf16(ahi, blo, acc, 0, 0, 0); acc = __builtin_amdgcn_mfma_f32_16x16x32_bf16(ahi, bhi, acc, 0, 0, 0);
;             float pr[4];
; #pragma unroll
;             for (int r = 0; r < 4; ++r) { const float lg = acc[r]; const float ls = fminf(lg, 0.f) - __logf(1.0f + __expf(-fabsf(lg))); pr[r] = ls * (1.0f / 16.0f) + (r ? pr[r - 1] : 0.f); }
;             const float T = pr[3];
;             const float u1 = __shfl_up(T, 16), s1 = T + (g >= 1 ? u1 : 0.f);
;             const float u2 = __shfl_up(s1, 32), s2 = s1 + (g >= 2 ? u2 : 0.f);
;             const float base = run + (s2 - T); run += __shfl(s2, 48 + fr);
; #pragma unroll
;             for (int r = 0; r < 4; ++r) *(LAS float*)(Lb + (16 * tt + 4 * g + r) * BP + (16 * w + fr) * 4) = base + pr[r];
;         }
	ds_read_b128 v[32:35], v96 offset:2048
	ds_read_b128 v[36:39], v96 offset:2064
	s_waitcnt lgkmcnt(1)
	v_cvt_pk_bf16_f32 v120, v32, v33
	v_lshlrev_b32_e32 v132, 16, v120
	v_and_b32_e32 v133, 0xffff0000, v120
	v_pk_add_f32 v[32:33], v[32:33], v[132:133] neg_lo:[0,1] neg_hi:[0,1]
	v_cvt_pk_bf16_f32 v121, v34, v35
	v_lshlrev_b32_e32 v134, 16, v121
	v_and_b32_e32 v135, 0xffff0000, v121
	v_pk_add_f32 v[34:35], v[34:35], v[134:135] neg_lo:[0,1] neg_hi:[0,1]
	s_waitcnt lgkmcnt(0)
	v_cvt_pk_bf16_f32 v122, v36, v37
	v_lshlrev_b32_e32 v136, 16, v122
	v_and_b32_e32 v137, 0xffff0000, v122
	v_pk_add_f32 v[36:37], v[36:37], v[136:137] neg_lo:[0,1] neg_hi:[0,1]
	v_cvt_pk_bf16_f32 v123, v38, v39
	v_lshlrev_b32_e32 v138, 16, v123
	v_and_b32_e32 v139, 0xffff0000, v123
	v_pk_add_f32 v[38:39], v[38:39], v[138:139] neg_lo:[0,1] neg_hi:[0,1]
	s_nop 0
	v_cvt_pk_bf16_f32 v119, v38, v39
	v_cvt_pk_bf16_f32 v118, v36, v37
	v_cvt_pk_bf16_f32 v117, v34, v35
	v_cvt_pk_bf16_f32 v116, v32, v33
.LBB0_490:
	s_or_b64 exec, exec, s[36:37]
	s_nop 0
	v_mfma_f32_16x16x32_bf16 v[32:35], v[116:119], v[20:23], v[28:31]
	s_waitcnt lgkmcnt(2)
	v_add_f32_e32 v40, v40, v41
	v_mfma_f32_16x16x32_bf16 v[32:35], v[120:123], v[24:27], v[32:35]
	v_mfma_f32_16x16x32_bf16 v[32:35], v[120:123], v[20:23], v[32:35]
	s_nop 7
	v_min_f32_e32 v36, 0, v32
	v_mul_f32_e64 v32, |v32|, s89
	v_exp_f32_e32 v32, v32
	v_mul_f32_e64 v37, |v33|, s89
	v_exp_f32_e32 v37, v37
	v_add_f32_e32 v32, 1.0, v32
	v_add_f32_e32 v37, 1.0, v37
	v_log_f32_e32 v32, v32
	v_log_f32_e32 v37, v37
	v_mul_f32_e32 v39, 0x3f317217, v32
	v_fma_f32 v39, v32, s91, -v39
	v_fmac_f32_e32 v39, 0x3377d1cf, v32
	v_fmac_f32_e32 v39, 0x3f317217, v32
	v_mul_f32_e32 v42, 0x3f317217, v37
	v_sub_f32_e32 v32, v36, v39
	v_fma_f32 v36, v37, s91, -v42
	v_fmac_f32_e32 v36, 0x3377d1cf, v37
	v_fmac_f32_e32 v36, 0x3f317217, v37
	v_min_f32_e32 v33, 0, v33
	v_mul_f32_e64 v37, |v34|, s89
	v_exp_f32_e32 v37, v37
	v_sub_f32_e32 v33, v33, v36
	v_add_f32_e32 v36, 1.0, v37
	v_min_f32_e32 v34, 0, v34
	v_fma_f32 v32, v32, s93, 0
	v_log_f32_e32 v36, v36
	v_fmamk_f32 v33, v33, 0x3d800000, v32
	v_mul_f32_e32 v37, 0x3f317217, v36
	v_fma_f32 v37, v36, s91, -v37
	v_fmac_f32_e32 v37, 0x3377d1cf, v36
	v_fmac_f32_e32 v37, 0x3f317217, v36
	s_nop 1
	v_mov_b32_e32 v36, v37
	v_mul_f32_e64 v37, |v35|, s89
	v_exp_f32_e32 v37, v37
	v_sub_f32_e32 v34, v34, v36
	v_add_f32_e32 v36, 1.0, v37
	v_min_f32_e32 v35, 0, v35
	v_fmamk_f32 v34, v34, 0x3d800000, v33
	v_log_f32_e32 v36, v36
	s_nop 0
	v_mul_f32_e32 v37, 0x3f317217, v36
	v_fma_f32 v37, v36, s91, -v37
	v_fmac_f32_e32 v37, 0x3377d1cf, v36
	v_fmac_f32_e32 v37, 0x3f317217, v36
	s_nop 1
	v_sub_f32_e32 v35, v35, v37
	v_fmamk_f32 v35, v35, 0x3d800000, v34
	ds_bpermute_b32 v36, v83, v35
	s_waitcnt lgkmcnt(0)
	v_cndmask_b32_e64 v36, v36, 0, s[8:9]
	v_add_f32_e32 v36, v36, v35
	ds_bpermute_b32 v37, v84, v36
	s_waitcnt lgkmcnt(0)
	v_cndmask_b32_e64 v37, 0, v37, s[10:11]
	v_add_f32_e32 v36, v37, v36
	v_sub_f32_e32 v37, v36, v35
	ds_bpermute_b32 v41, v85, v36
	v_add_f32_e32 v37, v40, v37
	v_add_f32_e32 v32, v32, v37
	v_add_f32_e32 v33, v33, v37
	v_add_u32_e32 v36, 0xca00, v98
	ds_write2_b32 v36, v32, v33 offset1:132
	v_add_f32_e32 v32, v34, v37
	v_add_f32_e32 v33, v35, v37
	v_add_u32_e32 v34, 0xce00, v98
	ds_write2_b32 v34, v32, v33 offset0:8 offset1:140
	v_mov_b32_e32 v124, 0
	v_mov_b32_e32 v125, 0
	v_mov_b32_e32 v126, 0
	v_mov_b32_e32 v127, 0
	v_mov_b32_e32 v128, 0
	v_mov_b32_e32 v129, 0
	v_mov_b32_e32 v130, 0
	v_mov_b32_e32 v131, 0
	s_and_saveexec_b64 s[36:37], s[6:7]
	s_cbranch_execz .LBB0_492
	ds_read_b128 v[32:35], v96 offset:3072
	ds_read_b128 v[36:39], v96 offset:3088
	s_waitcnt lgkmcnt(1)
	v_cvt_pk_bf16_f32 v128, v32, v33
	v_lshlrev_b32_e32 v132, 16, v128
	v_and_b32_e32 v133, 0xffff0000, v128
	v_pk_add_f32 v[32:33], v[32:33], v[132:133] neg_lo:[0,1] neg_hi:[0,1]
	v_cvt_pk_bf16_f32 v129, v34, v35
	v_lshlrev_b32_e32 v134, 16, v129
	v_and_b32_e32 v135, 0xffff0000, v129
	v_pk_add_f32 v[34:35], v[34:35], v[134:135] neg_lo:[0,1] neg_hi:[0,1]
	s_waitcnt lgkmcnt(0)
	v_cvt_pk_bf16_f32 v130, v36, v37
	v_lshlrev_b32_e32 v136, 16, v130
	v_and_b32_e32 v137, 0xffff0000, v130
	v_pk_add_f32 v[36:37], v[36:37], v[136:137] neg_lo:[0,1] neg_hi:[0,1]
	v_cvt_pk_bf16_f32 v131, v38, v39
	v_lshlrev_b32_e32 v138, 16, v131
	v_and_b32_e32 v139, 0xffff0000, v131
	v_pk_add_f32 v[38:39], v[38:39], v[138:139] neg_lo:[0,1] neg_hi:[0,1]
	s_nop 0
	v_cvt_pk_bf16_f32 v127, v38, v39
	v_cvt_pk_bf16_f32 v126, v36, v37
	v_cvt_pk_bf16_f32 v125, v34, v35
	v_cvt_pk_bf16_f32 v124, v32, v33
; #define LAS __attribute__((address_space(3)))
; __device__ __forceinline__ void phase_gla_pre(const Params& P, LAS unsigned char* lds, bool dry) {
;     ...
;         for (int tt = 0; tt < 4; ++tt) {
;             bf16x8 ahi = (bf16x8){0, 0, 0, 0, 0, 0, 0, 0}, alo = ahi;
;             if (g < 2) { const f32x4 l0 = *(const LAS f32x4*)(Llr + (16 * tt + fr) * 16 + 8 * g), l1 = *(const LAS f32x4*)(Llr + (16 * tt + fr) * 16 + 8 * g + 4); split8(l0, l1, ahi, alo); }
;             f32x4 acc = (f32x4){bg, bg, bg, bg};
;             acc = __builtin_amdgcn_mfma_f32_16x16x32_bf16(alo, bhi, acc, 0, 0, 0); acc = __builtin_amdgcn_mfma_f32_16x16x32_bf16(ahi, blo, acc, 0, 0, 0); acc = __builtin_amdgcn_mfma_f32_16x16x32_bf16(ahi, bhi, acc, 0, 0, 0);
;             float pr[4];
; #pragma unroll
;             for (int r = 0; r < 4; ++r) { const float lg = acc[r]; const float ls = fminf(lg, 0.f) - __logf(1.0f + __expf(-fabsf(lg))); pr[r] = ls * (1.0f / 16.0f) + (r ? pr[r - 1] : 0.f); }
;             const float T = pr[3];
;             const float u1 = __shfl_up(T, 16), s1 = T + (g >= 1 ? u1 : 0.f);
;             const float u2 = __shfl_up(s1, 32), s2 = s1 + (g >= 2 ? u2 : 0.f);
;             const float base = run + (s2 - T); run += __shfl(s2, 48 + fr);
; #pragma unroll
;             for (int r = 0; r < 4; ++r) *(LAS float*)(Lb + (16 * tt + 4 * g + r) * BP + (16 * w + fr) * 4) = base + pr[r];
;         }
;         __syncthreads();
;         {
;             f32x4 bb[4], bm[4], bl[4];
; #pragma unroll
;             for (int i = 0; i < 4; ++i) { bb[i] = *(const LAS f32x4*)(Lb + te * BP + (16 * kc + 4 * i) * 4); bm[i] = *(const LAS f32x4*)(Lb + 31 * BP + (16 * kc + 4 * i) * 4); bl[i] = *(const LAS f32x4*)(Lb + 63 * BP + (16 * kc + 4 * i) * 4); }
;             unsigned oqi[8], oki[8], oqd[8], oks[8];
; #pragma unroll
;             for (int e2 = 0; e2 < 8; ++e2) {
;                 const unsigned qw = e2 < 4 ? rq[0][e2] : rq[1][e2 - 4], kw = e2 < 4 ? rk[0][e2] : rk[1][e2 - 4];
;                 float vqi[2], vki[2], vqd[2], vks[2];
; #pragma unroll
;                 for (int hh = 0; hh < 2; ++hh) {
;                     const int e = 2 * e2 + hh; const float bv = bb[e >> 2][e & 3], bmv = bm[e >> 2][e & 3], blv = bl[e >> 2][e & 3];
;                     const float qv = hh ? bfhi(qw) : bflo(qw), kv = hh ? bfhi(kw) : bflo(kw);
;                     const float e1 = __expf(bv - bmv);
.LBB0_492:
	s_or_b64 exec, exec, s[36:37]
	s_nop 0
	v_mfma_f32_16x16x32_bf16 v[28:31], v[124:127], v[20:23], v[28:31]
	v_and_b32_e32 v111, 0xffff0000, v5
	v_and_b32_e32 v110, 0xffff0000, v4
	v_and_b32_e32 v117, 0xffff0000, v13
	v_mfma_f32_16x16x32_bf16 v[24:27], v[128:131], v[24:27], v[28:31]
	v_and_b32_e32 v116, 0xffff0000, v12
	v_and_b32_e32 v121, 0xffff0000, v7
	v_and_b32_e32 v120, 0xffff0000, v6
	v_mfma_f32_16x16x32_bf16 v[20:23], v[128:131], v[20:23], v[24:27]
	v_and_b32_e32 v127, 0xffff0000, v17
	v_and_b32_e32 v126, 0xffff0000, v16
	v_lshlrev_b32_e32 v125, 16, v17
	v_lshlrev_b32_e32 v124, 16, v16
	v_lshlrev_b32_e32 v133, 16, v11
	s_nop 2
	v_min_f32_e32 v24, 0, v20
	v_mul_f32_e64 v20, |v20|, s89
	v_exp_f32_e32 v20, v20
	v_mul_f32_e64 v25, |v21|, s89
	v_exp_f32_e32 v25, v25
	v_add_f32_e32 v20, 1.0, v20
	v_add_f32_e32 v25, 1.0, v25
	v_log_f32_e32 v20, v20
	v_log_f32_e32 v25, v25
	v_mul_f32_e32 v27, 0x3f317217, v20
	v_fma_f32 v27, v20, s91, -v27
	v_fmac_f32_e32 v27, 0x3377d1cf, v20
	v_fmac_f32_e32 v27, 0x3f317217, v20
	v_mul_f32_e32 v28, 0x3f317217, v25
	v_sub_f32_e32 v20, v24, v27
	v_fma_f32 v24, v25, s91, -v28
	v_fmac_f32_e32 v24, 0x3377d1cf, v25
	v_fmac_f32_e32 v24, 0x3f317217, v25
	v_min_f32_e32 v21, 0, v21
	v_mul_f32_e64 v25, |v22|, s89
	v_exp_f32_e32 v25, v25
	v_sub_f32_e32 v21, v21, v24
	v_add_f32_e32 v24, 1.0, v25
	v_min_f32_e32 v22, 0, v22
	v_fma_f32 v20, v20, s93, 0
	v_log_f32_e32 v24, v24
	v_fmamk_f32 v21, v21, 0x3d800000, v20
	v_lshlrev_b32_e32 v132, 16, v10
	v_mul_f32_e32 v25, 0x3f317217, v24
	v_fma_f32 v25, v24, s91, -v25
	v_fmac_f32_e32 v25, 0x3377d1cf, v24
	v_fmac_f32_e32 v25, 0x3f317217, v24
	v_and_b32_e32 v135, 0xffff0000, v11
	v_and_b32_e32 v134, 0xffff0000, v10
	v_mov_b32_e32 v24, v25
	v_mul_f32_e64 v25, |v23|, s89
	v_exp_f32_e32 v25, v25
	v_sub_f32_e32 v22, v22, v24
	v_add_f32_e32 v24, 1.0, v25
	v_min_f32_e32 v23, 0, v23
	v_fmamk_f32 v22, v22, 0x3d800000, v21
	v_log_f32_e32 v24, v24
	s_waitcnt lgkmcnt(2)
	v_add_f32_e32 v26, v40, v41
	s_and_b32 s74, s1, 0xfc0
	s_ashr_i32 s83, s82, 31
	v_mul_f32_e32 v25, 0x3f317217, v24
	v_fma_f32 v25, v24, s91, -v25
	v_fmac_f32_e32 v25, 0x3377d1cf, v24
	v_fmac_f32_e32 v25, 0x3f317217, v24
	s_nop 1
	v_sub_f32_e32 v23, v23, v25
	v_fmamk_f32 v23, v23, 0x3d800000, v22
	ds_bpermute_b32 v24, v83, v23
	s_lshl_b64 s[36:37], s[82:83], 20
	s_waitcnt lgkmcnt(0)
	v_cndmask_b32_e64 v24, v24, 0, s[8:9]
	v_add_f32_e32 v24, v24, v23
	ds_bpermute_b32 v25, v84, v24
	s_waitcnt lgkmcnt(0)
	v_cndmask_b32_e64 v25, 0, v25, s[10:11]
	v_add_f32_e32 v24, v25, v24
	v_sub_f32_e32 v24, v24, v23
	v_add_f32_e32 v24, v26, v24
	v_add_f32_e32 v20, v20, v24
	v_add_f32_e32 v21, v21, v24
	v_add_u32_e32 v25, 0xea00, v98
	ds_write2_b32 v25, v20, v21 offset0:64 offset1:196
	v_add_f32_e32 v20, v22, v24
	v_add_f32_e32 v21, v23, v24
	v_add_u32_e32 v22, 0xee00, v98
	ds_write2_b32 v22, v20, v21 offset0:72 offset1:204
	v_add_u32_e32 v22, s94, v87
	s_waitcnt lgkmcnt(0)
	s_barrier
	v_add_u32_e32 v20, v86, v87
	v_add_u32_e32 v21, 0, v87
	ds_read_b128 v[32:35], v22
	ds_read_b128 v[24:27], v89
	ds_read_b128 v[60:63], v21 offset:51184
	ds_read_b128 v[64:67], v20 offset:34816
	ds_read_b128 v[74:77], v20 offset:34832
	ds_read_b128 v[44:47], v20 offset:34848
	ds_read_b128 v[36:39], v20 offset:34864
	ds_read_b128 v[100:103], v21 offset:51200
	s_waitcnt lgkmcnt(4)
	v_sub_f32_e32 v61, v65, v61
	v_mul_f32_e32 v61, 0x3fb8aa3b, v61
	v_sub_f32_e32 v63, v67, v63
	v_exp_f32_e32 v72, v61
	v_sub_f32_e32 v61, v32, v64
	v_mul_f32_e32 v63, 0x3fb8aa3b, v63
	v_mul_f32_e32 v61, 0x3fb8aa3b, v61
	v_exp_f32_e32 v73, v63
	v_exp_f32_e32 v78, v61
	v_mul_f32_e32 v61, 0x3fb8aa3b, v65
	v_sub_f32_e32 v20, v64, v60
	v_exp_f32_e32 v108, v61
	v_sub_f32_e32 v61, v66, v62
	v_mul_f32_e32 v20, 0x3fb8aa3b, v20
	v_mul_f32_e32 v69, 0x3fb8aa3b, v64
	v_mul_f32_e32 v61, 0x3fb8aa3b, v61
	v_sub_f32_e32 v62, v33, v65
	v_mul_f32_e32 v65, 0x3fb8aa3b, v66
	v_sub_f32_e32 v63, v34, v66
	v_exp_f32_e32 v60, v20
	v_exp_f32_e32 v70, v69
	v_rcp_f32_e32 v64, v72
	v_exp_f32_e32 v61, v61
	v_exp_f32_e32 v71, v65
	v_mul_f32_e32 v63, 0x3fb8aa3b, v63
	v_rcp_f32_e32 v65, v73
	v_exp_f32_e32 v79, v63
	v_mul_f32_e32 v63, 0x3fb8aa3b, v67
	v_exp_f32_e32 v109, v63
	v_sub_f32_e32 v63, v35, v67
	v_lshlrev_b32_e32 v67, 16, v5
	v_lshlrev_b32_e32 v66, 16, v4
	v_pk_mul_f32 v[112:113], v[60:61], v[66:67]
	v_pk_mul_f32 v[114:115], v[72:73], v[110:111]
	v_pk_mul_f32 v[72:73], v[64:65], v[116:117]
	v_pk_mul_f32 v[64:65], v[70:71], v[66:67]
	s_waitcnt lgkmcnt(0)
	v_sub_f32_e32 v66, v74, v100
	v_mul_f32_e32 v66, 0x3fb8aa3b, v66
	v_mul_f32_e32 v71, 0x3fb8aa3b, v74
	v_exp_f32_e32 v70, v66
	v_pk_mul_f32 v[66:67], v[108:109], v[110:111]
	v_exp_f32_e32 v108, v71
	v_sub_f32_e32 v71, v75, v101
	v_mul_f32_e32 v71, 0x3fb8aa3b, v71
	v_mul_f32_e32 v62, 0x3fb8aa3b, v62
	v_mul_f32_e32 v63, 0x3fb8aa3b, v63
	v_exp_f32_e32 v100, v71
	v_sub_f32_e32 v71, v24, v74
	v_exp_f32_e32 v62, v62
	v_exp_f32_e32 v63, v63
	v_mul_f32_e32 v71, 0x3fb8aa3b, v71
	v_exp_f32_e32 v74, v71
	v_mul_f32_e32 v71, 0x3fb8aa3b, v75
	v_sub_f32_e32 v75, v25, v75
	v_mul_f32_e32 v75, 0x3fb8aa3b, v75
	v_exp_f32_e32 v118, v75
	v_mul_f32_e32 v75, 0x3fb8aa3b, v76
	v_pk_mul_f32 v[62:63], v[62:63], v[116:117]
	v_exp_f32_e32 v116, v71
	v_sub_f32_e32 v71, v76, v102
	v_exp_f32_e32 v109, v75
	v_sub_f32_e32 v75, v77, v103
	v_mul_f32_e32 v71, 0x3fb8aa3b, v71
	v_mul_f32_e32 v75, 0x3fb8aa3b, v75
	v_rcp_f32_e32 v68, v60
	v_rcp_f32_e32 v69, v61
	v_exp_f32_e32 v71, v71
	v_exp_f32_e32 v101, v75
	v_sub_f32_e32 v75, v26, v76
	v_mul_f32_e32 v76, 0x3fb8aa3b, v77
	v_exp_f32_e32 v117, v76
	v_sub_f32_e32 v76, v27, v77
	v_mul_f32_e32 v76, 0x3fb8aa3b, v76
	v_lshlrev_b32_e32 v61, 16, v13
	v_lshlrev_b32_e32 v60, 16, v12
	v_exp_f32_e32 v119, v76
	v_lshlrev_b32_e32 v77, 16, v7
	v_lshlrev_b32_e32 v76, 16, v6
	v_pk_mul_f32 v[68:69], v[68:69], v[60:61]
	v_pk_mul_f32 v[60:61], v[78:79], v[60:61]
	v_rcp_f32_e32 v78, v70
	v_rcp_f32_e32 v110, v100
	v_rcp_f32_e32 v79, v71
	v_rcp_f32_e32 v111, v101
	v_pk_mul_f32 v[70:71], v[70:71], v[76:77]
	v_pk_mul_f32 v[100:101], v[100:101], v[120:121]
	v_cvt_pk_bf16_f32 v224, v112, v114
	v_cvt_pk_bf16_f32 v222, v113, v115
	v_cvt_pk_bf16_f32 v221, v70, v100
	v_cvt_pk_bf16_f32 v220, v71, v101
	ds_read_b128 v[104:107], v21 offset:51216
	ds_read_b128 v[40:43], v21 offset:51232
	ds_read_b128 v[28:31], v90
	ds_read_b128 v[20:23], v91
	v_mov_b32_e32 v103, v220
	v_mov_b32_e32 v102, v221
	v_lshlrev_b32_e32 v71, 16, v15
	v_lshlrev_b32_e32 v70, 16, v14
	v_mul_f32_e32 v75, 0x3fb8aa3b, v75
	v_mov_b32_e32 v101, v222
	v_mov_b32_e32 v100, v224
	v_pk_mul_f32 v[114:115], v[78:79], v[70:71]
	s_waitcnt lgkmcnt(3)
; #define LAS __attribute__((address_space(3)))
; __device__ __forceinline__ float bflo(unsigned w) { return __uint_as_float(w << 16); }
; __device__ __forceinline__ float bfhi(unsigned w) { return __uint_as_float(w & 0xffff0000u); }
; __device__ __forceinline__ unsigned pk2(float lo, float hi) { return f2bf(lo) | (f2bf(hi) << 16); }
; __device__ __forceinline__ void phase_gla_pre(const Params& P, LAS unsigned char* lds, bool dry) {
;     ...
;             for (int e2 = 0; e2 < 8; ++e2) {
;                 const unsigned qw = e2 < 4 ? rq[0][e2] : rq[1][e2 - 4], kw = e2 < 4 ? rk[0][e2] : rk[1][e2 - 4];
;                 float vqi[2], vki[2], vqd[2], vks[2];
; #pragma unroll
;                 for (int hh = 0; hh < 2; ++hh) {
;                     const int e = 2 * e2 + hh; const float bv = bb[e >> 2][e & 3], bmv = bm[e >> 2][e & 3], blv = bl[e >> 2][e & 3];
;                     const float qv = hh ? bfhi(qw) : bflo(qw), kv = hh ? bfhi(kw) : bflo(kw);
;                     const float e1 = __expf(bv - bmv);
;                     vqi[hh] = qv * e1; vki[hh] = kv * __builtin_amdgcn_rcpf(e1); vqd[hh] = qv * __expf(bv); vks[hh] = kv * __expf(blv - bv);
;                 }
;                 oqi[e2] = pk2(vqi[0], vqi[1]); oki[e2] = pk2(vki[0], vki[1]); oqd[e2] = pk2(vqd[0], vqd[1]); oks[e2] = pk2(vks[0], vks[1]);
;             }
;             *(LAS u32x4*)(Lqi + te * QP + 32 * kc) = (u32x4){oqi[0], oqi[1], oqi[2], oqi[3]}; *(LAS u32x4*)(Lqi + te * QP + 32 * kc + 16) = (u32x4){oqi[4], oqi[5], oqi[6], oqi[7]};
;             *(LAS u32x4*)(Lki + te * QP + 32 * kc) = (u32x4){oki[0], oki[1], oki[2], oki[3]}; *(LAS u32x4*)(Lki + te * QP + 32 * kc + 16) = (u32x4){oki[4], oki[5], oki[6], oki[7]};
;             if (!dry) {
;                 bf16_t* p_ = PJ + ((size_t)bh * SEQ + c * 64 + te) * 128 + 16 * kc;
;                 *(u32x4*)(p_ + T_Q) = (u32x4){oqd[0], oqd[1], oqd[2], oqd[3]}; *(u32x4*)(p_ + T_Q + 8) = (u32x4){oqd[4], oqd[5], oqd[6], oqd[7]};
;                 *(u32x4*)(p_ + T_K) = (u32x4){oks[0], oks[1], oks[2], oks[3]}; *(u32x4*)(p_ + T_K + 8) = (u32x4){oks[4], oks[5], oks[6], oks[7]};
;                 if (te == 63) {
; #pragma unroll
;                     for (int i = 0; i < 4; ++i) *(f32x4*)(DEC + (size_t)item * 128 + 16 * kc + 4 * i) = (f32x4){__expf(bl[i][0]), __expf(bl[i][1]), __expf(bl[i][2]), __expf(bl[i][3])};
;                 }
	v_sub_f32_e32 v78, v44, v104
	v_sub_f32_e32 v105, v45, v105
	v_exp_f32_e32 v75, v75
	v_mul_f32_e32 v78, 0x3fb8aa3b, v78
	v_mul_f32_e32 v105, 0x3fb8aa3b, v105
	v_exp_f32_e32 v104, v78
	v_pk_mul_f32 v[78:79], v[116:117], v[120:121]
	v_exp_f32_e32 v116, v105
	v_mul_f32_e32 v105, 0x3fb8aa3b, v45
	s_waitcnt lgkmcnt(1)
	v_sub_f32_e32 v45, v29, v45
	v_mul_f32_e32 v45, 0x3fb8aa3b, v45
	v_and_b32_e32 v113, 0xffff0000, v15
	v_and_b32_e32 v112, 0xffff0000, v14
	v_exp_f32_e32 v120, v105
	v_sub_f32_e32 v105, v46, v106
	v_exp_f32_e32 v106, v45
	v_mul_f32_e32 v45, 0x3fb8aa3b, v46
	v_pk_mul_f32 v[110:111], v[110:111], v[112:113]
	v_pk_mul_f32 v[70:71], v[74:75], v[70:71]
	v_pk_mul_f32 v[74:75], v[118:119], v[112:113]
	v_exp_f32_e32 v113, v45
	v_sub_f32_e32 v45, v47, v107
	v_mul_f32_e32 v45, 0x3fb8aa3b, v45
	v_exp_f32_e32 v117, v45
	v_sub_f32_e32 v45, v30, v46
	v_mul_f32_e32 v46, 0x3fb8aa3b, v47
	v_exp_f32_e32 v121, v46
	v_sub_f32_e32 v46, v31, v47
	v_pk_mul_f32 v[76:77], v[108:109], v[76:77]
	v_mul_f32_e32 v109, 0x3fb8aa3b, v44
	v_mul_f32_e32 v105, 0x3fb8aa3b, v105
	v_mul_f32_e32 v46, 0x3fb8aa3b, v46
	v_exp_f32_e32 v112, v109
	v_exp_f32_e32 v105, v105
	v_exp_f32_e32 v107, v46
	v_rcp_f32_e32 v118, v116
	v_rcp_f32_e32 v119, v117
	v_sub_f32_e32 v44, v28, v44
	v_lshlrev_b32_e32 v47, 16, v9
	v_lshlrev_b32_e32 v46, 16, v8
	v_rcp_f32_e32 v108, v104
	v_mul_f32_e32 v44, 0x3fb8aa3b, v44
	v_rcp_f32_e32 v109, v105
	v_mul_f32_e32 v45, 0x3fb8aa3b, v45
	v_pk_mul_f32 v[104:105], v[104:105], v[46:47]
	v_pk_mul_f32 v[112:113], v[112:113], v[46:47]
	v_sub_f32_e32 v40, v36, v40
	v_pk_mul_f32 v[46:47], v[106:107], v[126:127]
	v_mul_f32_e32 v107, 0x3fb8aa3b, v36
	s_waitcnt lgkmcnt(0)
	v_sub_f32_e32 v36, v20, v36
	v_exp_f32_e32 v44, v44
	v_exp_f32_e32 v45, v45
	v_mul_f32_e32 v36, 0x3fb8aa3b, v36
	v_pk_mul_f32 v[118:119], v[118:119], v[126:127]
	v_exp_f32_e32 v126, v36
	v_mul_f32_e32 v36, 0x3fb8aa3b, v37
	v_sub_f32_e32 v41, v37, v41
	v_exp_f32_e32 v130, v36
	v_sub_f32_e32 v36, v38, v42
	v_mul_f32_e32 v41, 0x3fb8aa3b, v41
	v_mul_f32_e32 v36, 0x3fb8aa3b, v36
	v_pk_mul_f32 v[108:109], v[108:109], v[124:125]
	v_pk_mul_f32 v[44:45], v[44:45], v[124:125]
	v_exp_f32_e32 v124, v41
	v_exp_f32_e32 v41, v36
	v_sub_f32_e32 v36, v21, v37
	v_mul_f32_e32 v36, 0x3fb8aa3b, v36
	v_and_b32_e32 v123, 0xffff0000, v9
	v_and_b32_e32 v122, 0xffff0000, v8
	v_exp_f32_e32 v42, v36
	v_mul_f32_e32 v36, 0x3fb8aa3b, v38
	v_pk_mul_f32 v[116:117], v[116:117], v[122:123]
	v_pk_mul_f32 v[120:121], v[120:121], v[122:123]
	v_exp_f32_e32 v123, v36
	v_sub_f32_e32 v36, v39, v43
	v_mul_f32_e32 v36, 0x3fb8aa3b, v36
	v_mul_f32_e32 v40, 0x3fb8aa3b, v40
	v_exp_f32_e32 v125, v36
	v_sub_f32_e32 v36, v22, v38
	v_exp_f32_e32 v40, v40
	v_mul_f32_e32 v36, 0x3fb8aa3b, v36
	v_exp_f32_e32 v127, v36
	v_mul_f32_e32 v36, 0x3fb8aa3b, v39
	v_exp_f32_e32 v131, v36
	v_sub_f32_e32 v36, v23, v39
	v_mul_f32_e32 v36, 0x3fb8aa3b, v36
	v_rcp_f32_e32 v128, v124
	v_rcp_f32_e32 v129, v125
	v_exp_f32_e32 v43, v36
	v_pk_mul_f32 v[36:37], v[40:41], v[132:133]
	v_pk_mul_f32 v[38:39], v[124:125], v[134:135]
	v_rcp_f32_e32 v106, v40
	v_exp_f32_e32 v122, v107
	v_rcp_f32_e32 v107, v41
	v_cvt_pk_bf16_f32 v228, v104, v116
	v_cvt_pk_bf16_f32 v227, v105, v117
	v_cvt_pk_bf16_f32 v226, v36, v38
	v_cvt_pk_bf16_f32 v225, v37, v39
	v_mov_b32_e32 v39, v225
	v_mov_b32_e32 v38, v226
	v_mov_b32_e32 v37, v227
	v_mov_b32_e32 v36, v228
	ds_write_b128 v92, v[100:103]
	ds_write_b128 v92, v[36:39] offset:16
	v_cvt_pk_bf16_f32 v230, v68, v72
	v_cvt_pk_bf16_f32 v229, v69, v73
	v_lshlrev_b32_e32 v41, 16, v19
	v_lshlrev_b32_e32 v40, 16, v18
	v_cvt_pk_bf16_f32 v39, v115, v111
	v_cvt_pk_bf16_f32 v38, v114, v110
	v_mov_b32_e32 v37, v229
	v_mov_b32_e32 v36, v230
	v_and_b32_e32 v105, 0xffff0000, v19
	v_and_b32_e32 v104, 0xffff0000, v18
	v_pk_mul_f32 v[106:107], v[106:107], v[40:41]
	ds_write_b128 v92, v[36:39] offset:17408
	v_pk_mul_f32 v[116:117], v[128:129], v[104:105]
	s_nop 0
	v_cvt_pk_bf16_f32 v39, v107, v117
	v_cvt_pk_bf16_f32 v38, v106, v116
	v_cvt_pk_bf16_f32 v37, v109, v119
	v_cvt_pk_bf16_f32 v36, v108, v118
	ds_write_b128 v92, v[36:39] offset:17424
	v_lshl_add_u64 v[36:37], s[74:75], 0, v[48:49]
	v_lshlrev_b64 v[36:37], 8, v[36:37]
	v_lshl_add_u64 v[38:39], v[52:53], 0, s[36:37]
	v_lshl_add_u64 v[68:69], v[38:39], 0, v[36:37]
	v_cvt_pk_bf16_f32 v232, v64, v66
	v_cvt_pk_bf16_f32 v233, v65, v67
	s_brev_b32 s36, 16
	v_cvt_pk_bf16_f32 v39, v77, v79
	v_mov_b32_e32 v36, v232
	v_add_co_u32_e32 v64, vcc, s36, v68
	v_cvt_pk_bf16_f32 v38, v76, v78
	v_mov_b32_e32 v37, v233
	v_addc_co_u32_e32 v65, vcc, 0, v69, vcc
	v_pk_mul_f32 v[122:123], v[122:123], v[132:133]
	global_store_dwordx4 v[64:65], v[36:39], off
	v_pk_mul_f32 v[124:125], v[130:131], v[134:135]
	s_nop 0
	v_cvt_pk_bf16_f32 v39, v123, v125
	v_cvt_pk_bf16_f32 v38, v122, v124
	v_cvt_pk_bf16_f32 v37, v113, v121
	v_cvt_pk_bf16_f32 v36, v112, v120
	global_store_dwordx4 v[64:65], v[36:39], off offset:16
	s_nop 1
	s_nop 0
	v_cvt_pk_bf16_f32 v234, v60, v62
	v_cvt_pk_bf16_f32 v235, v61, v63
	v_cvt_pk_bf16_f32 v39, v71, v75
	v_mov_b32_e32 v36, v234
	v_add_co_u32_e32 v60, vcc, s95, v68
	v_pk_mul_f32 v[42:43], v[42:43], v[104:105]
	v_cvt_pk_bf16_f32 v38, v70, v74
	v_mov_b32_e32 v37, v235
	v_addc_co_u32_e32 v61, vcc, 0, v69, vcc
	v_pk_mul_f32 v[40:41], v[126:127], v[40:41]
	global_store_dwordx4 v[60:61], v[36:39], off
	s_nop 1
	v_cvt_pk_bf16_f32 v240, v44, v46
	v_cvt_pk_bf16_f32 v239, v45, v47
	v_cvt_pk_bf16_f32 v238, v40, v42
	v_cvt_pk_bf16_f32 v237, v41, v43
	v_mov_b32_e32 v39, v237
	v_mov_b32_e32 v38, v238
	v_mov_b32_e32 v37, v239
	v_mov_b32_e32 v36, v240
	global_store_dwordx4 v[60:61], v[36:39], off offset:16
	s_and_saveexec_b64 s[36:37], s[12:13]
	s_cbranch_execz .LBB0_494
	v_mul_f32_e32 v32, 0x3fb8aa3b, v32
	v_mul_f32_e32 v33, 0x3fb8aa3b, v33
	v_mul_f32_e32 v34, 0x3fb8aa3b, v34
	v_mul_f32_e32 v35, 0x3fb8aa3b, v35
	v_exp_f32_e32 v32, v32
	v_exp_f32_e32 v33, v33
	v_exp_f32_e32 v34, v34
	v_exp_f32_e32 v35, v35
	v_mul_f32_e32 v24, 0x3fb8aa3b, v24
	v_mul_f32_e32 v25, 0x3fb8aa3b, v25
	v_mul_f32_e32 v26, 0x3fb8aa3b, v26
	v_mul_f32_e32 v27, 0x3fb8aa3b, v27
	s_ashr_i32 s81, s80, 31
	v_exp_f32_e32 v24, v24
	v_exp_f32_e32 v25, v25
	v_exp_f32_e32 v26, v26
	v_exp_f32_e32 v27, v27
	v_mul_f32_e32 v28, 0x3fb8aa3b, v28
	v_mul_f32_e32 v29, 0x3fb8aa3b, v29
	v_mul_f32_e32 v30, 0x3fb8aa3b, v30
	v_mul_f32_e32 v31, 0x3fb8aa3b, v31
	s_lshl_b64 s[42:43], s[80:81], 9
	v_exp_f32_e32 v28, v28
	v_exp_f32_e32 v29, v29
	v_exp_f32_e32 v30, v30
	v_exp_f32_e32 v31, v31
	v_mul_f32_e32 v20, 0x3fb8aa3b, v20
	v_mul_f32_e32 v21, 0x3fb8aa3b, v21
	v_mul_f32_e32 v22, 0x3fb8aa3b, v22
	v_mul_f32_e32 v23, 0x3fb8aa3b, v23
	v_lshl_add_u64 v[36:37], v[54:55], 0, s[42:43]
	v_exp_f32_e32 v20, v20
	v_exp_f32_e32 v21, v21
	v_exp_f32_e32 v22, v22
	v_exp_f32_e32 v23, v23
	global_store_dwordx4 v[36:37], v[32:35], off
	global_store_dwordx4 v[36:37], v[24:27], off offset:16
	global_store_dwordx4 v[36:37], v[28:31], off offset:32
	global_store_dwordx4 v[36:37], v[20:23], off offset:48
